# plus: top-k radix counting via v_cmp + s_bcnt1 (wave totals in SGPRs, no bpermute tree); router row loads and norm/shift/scale loads batched (2 waits per row instead of 7)
# baseline (speedup 1.0000x reference)
; __device__ __forceinline__ unsigned pack2(float a, float b) { return (unsigned)f2bf(a) | ((unsigned)f2bf(b) << 16); }
; __device__ __forceinline__ void router_rows(const Params& p, char* smem, int l, int nrows) {
;     ...
;     for (int rr = 0; rr < 2; ++rr) {
;       const int rl = wid * 2 + rr;
;       const int row = grp * 8 + rl;
;       const float* src = XR + (size_t)row * 1024;
;       int v = row < MLAT ? (row >> 13) : 2;
;       const float* mods = (const float*)(ws + OFF_MODS) + (l * 3 + v) * 6144;
;       float4 xv[4];
;       float ss = 0.f;
; #pragma unroll
;       for (int q = 0; q < 4; ++q) {
;         xv[q] = *(const float4*)&src[lane * 4 + 256 * q];
;         ss += xv[q].x * xv[q].x + xv[q].y * xv[q].y + xv[q].z * xv[q].z + xv[q].w * xv[q].w;
;       }
;       ss = wave_sum(ss);
;       float rstd = rsqrtf(ss * (1.f / 1024.f) + EPSF);
; #pragma unroll
;       for (int q = 0; q < 4; ++q) {
;         int col = lane * 4 + 256 * q;
;         float4 w = *(const float4*)&nw[col];
;         float4 sh = *(const float4*)&mods[3072 + col];
;         float4 sc = *(const float4*)&mods[4096 + col];
;         float h0 = xv[q].x * rstd * w.x * (1.f + sc.x) + sh.x;
;         float h1 = xv[q].y * rstd * w.y * (1.f + sc.y) + sh.y;
;         float h2 = xv[q].z * rstd * w.z * (1.f + sc.z) + sh.z;
;         float h3 = xv[q].w * rstd * w.w * (1.f + sc.w) + sh.w;
;         uint2 o; o.x = pack2(h0, h1); o.y = pack2(h2, h3);
;         *(uint2*)&H2[(size_t)row * 1024 + col] = o;
;         *(float4*)&Hs[(col >> 2) * 36 + rl * 4] = make_float4(h0, h1, h2, h3);
;       }
.LBB0_1270:
	s_lshl_b32 s6, s9, 3
	v_add_u32_e32 v2, s6, v33
	v_min_i32_e32 v4, 0x4000, v2
	v_ashrrev_i32_e32 v4, 13, v4
	v_add_u32_e32 v4, s8, v4
	s_movk_i32 s7, 0x1800
	v_mul_lo_u32 v4, v4, s7
	v_ashrrev_i32_e32 v5, 31, v4
	v_lshl_add_u64 v[4:5], v[4:5], 2, v[22:23]
	s_movk_i32 s5, 0x3000
	v_add_co_u32_e32 v30, vcc, s5, v4
	v_ashrrev_i32_e32 v3, 31, v2
	s_nop 0
	v_addc_co_u32_e32 v31, vcc, 0, v5, vcc
	v_lshlrev_b64 v[6:7], 12, v[2:3]
	v_add_co_u32_e32 v28, vcc, s91, v4
	v_lshl_add_u64 v[74:75], v[20:21], 0, v[6:7]
	v_lshlrev_b64 v[2:3], 11, v[2:3]
	v_addc_co_u32_e32 v29, vcc, 0, v5, vcc
	s_barrier
	v_lshl_add_u64 v[26:27], v[24:25], 0, v[2:3]
	global_load_dwordx4 v[186:189], v[74:75], off
	global_load_dwordx4 v[190:193], v[18:19], off
	global_load_dwordx4 v[212:215], v[30:31], off
	global_load_dwordx4 v[216:219], v[28:29], off
	global_load_dwordx4 v[220:223], v[74:75], off offset:2048
	global_load_dwordx4 v[224:227], v[74:75], off offset:1024
	global_load_dwordx4 v[228:231], v[74:75], off offset:3072
	global_load_dwordx4 v[232:235], v[18:19], off offset:1024
	global_load_dwordx4 v[240:243], v[30:31], off offset:1024
	global_load_dwordx4 v[244:247], v[28:29], off offset:1024
	global_load_dwordx4 v[248:251], v[18:19], off offset:2048
	global_load_dwordx4 v[252:255], v[30:31], off offset:2048
	s_waitcnt vmcnt(0)
	s_mov_b32 s4, 0x800000
	s_mov_b32 s92, 0x800000
	s_waitcnt lgkmcnt(0)
	v_mov_b32_e32 v40, v186
	v_mov_b32_e32 v42, v190
	v_mov_b32_e32 v43, v192
	v_mov_b32_e32 v39, v218
	v_mov_b32_e32 v4, v217
	v_mov_b32_e32 v8, v191
	v_mov_b32_e32 v5, v219
	v_pk_add_f32 v[50:51], v[4:5], 1.0 op_sel_hi:[1,0]
	v_mov_b32_e32 v46, v212
	v_mov_b32_e32 v47, v214
	v_mov_b32_e32 v12, v213
	v_mov_b32_e32 v10, v187
	v_mov_b32_e32 v38, v216
	v_mov_b32_e32 v2, v186
	v_pk_add_f32 v[44:45], v[38:39], 1.0 op_sel_hi:[1,0]
	v_mov_b32_e32 v41, v188
	v_mov_b32_e32 v48, v187
	v_mov_b32_e32 v49, v189
	v_mov_b32_e32 v34, v221
	v_mov_b32_e32 v35, v223
	s_waitcnt lgkmcnt(0)
	v_mov_b32_e32 v11, v225
	v_mov_b32_e32 v3, v224
	v_pk_mul_f32 v[10:11], v[10:11], v[10:11]
	v_mov_b32_e32 v38, v224
	v_pk_fma_f32 v[2:3], v[2:3], v[2:3], v[10:11]
	v_mov_b32_e32 v10, v188
	v_mov_b32_e32 v11, v226
	v_pk_fma_f32 v[2:3], v[10:11], v[10:11], v[2:3]
	v_mov_b32_e32 v10, v189
	v_mov_b32_e32 v11, v227
	v_pk_fma_f32 v[10:11], v[10:11], v[10:11], v[2:3]
	v_mov_b32_e32 v39, v226
	v_mov_b32_e32 v6, v225
	v_mov_b32_e32 v36, v220
	v_mov_b32_e32 v74, v220
	v_mov_b32_e32 v70, v221
	v_mov_b32_e32 v37, v222
	v_add_f32_e32 v10, v10, v11
	s_waitcnt lgkmcnt(0)
	v_mov_b32_e32 v71, v229
	v_mov_b32_e32 v75, v228
	v_pk_mul_f32 v[70:71], v[70:71], v[70:71]
	s_nop 0
	v_pk_fma_f32 v[70:71], v[74:75], v[74:75], v[70:71]
	v_mov_b32_e32 v74, v222
	v_mov_b32_e32 v75, v230
	v_pk_fma_f32 v[70:71], v[74:75], v[74:75], v[70:71]
	v_mov_b32_e32 v72, v223
	v_mov_b32_e32 v73, v231
	v_pk_fma_f32 v[70:71], v[72:73], v[72:73], v[70:71]
	s_nop 0
	v_add_f32_e32 v10, v10, v70
	v_add_f32_e32 v10, v10, v71
	ds_bpermute_b32 v11, v52, v10
	s_waitcnt lgkmcnt(0)
	v_add_f32_e32 v10, v10, v11
	ds_bpermute_b32 v11, v53, v10
	s_waitcnt lgkmcnt(0)
	v_add_f32_e32 v10, v10, v11
	ds_bpermute_b32 v11, v54, v10
	s_waitcnt lgkmcnt(0)
	v_add_f32_e32 v10, v10, v11
	ds_bpermute_b32 v11, v55, v10
	s_waitcnt lgkmcnt(0)
	v_add_f32_e32 v10, v10, v11
	ds_bpermute_b32 v11, v56, v10
	s_waitcnt lgkmcnt(0)
	v_add_f32_e32 v10, v10, v11
	ds_bpermute_b32 v11, v57, v10
	s_waitcnt lgkmcnt(0)
	v_add_f32_e32 v10, v10, v11
	v_fmamk_f32 v10, v10, 0x3a800000, v197
	v_cmp_gt_f32_e32 vcc, s4, v10
	v_mul_f32_e32 v11, 0x4b800000, v10
	s_nop 0
	v_cndmask_b32_e32 v10, v10, v11, vcc
	v_rsq_f32_e32 v10, v10
	s_nop 0
	v_mul_f32_e32 v11, 0x45800000, v10
	v_cndmask_b32_e32 v32, v10, v11, vcc
	v_pk_mul_f32 v[10:11], v[40:41], v[32:33] op_sel_hi:[1,0]
	v_mov_b32_e32 v7, v227
	v_pk_mul_f32 v[6:7], v[6:7], v[32:33] op_sel_hi:[1,0]
	v_pk_mul_f32 v[10:11], v[42:43], v[10:11]
	v_pk_mul_f32 v[36:37], v[36:37], v[32:33] op_sel_hi:[1,0]
	v_pk_fma_f32 v[40:41], v[44:45], v[10:11], v[46:47]
	v_pk_mul_f32 v[10:11], v[48:49], v[32:33] op_sel_hi:[1,0]
	v_pk_mul_f32 v[34:35], v[34:35], v[32:33] op_sel_hi:[1,0]
	v_mov_b32_e32 v9, v193
	v_pk_mul_f32 v[8:9], v[8:9], v[10:11]
	s_nop 0
	v_mov_b32_e32 v13, v215
	v_pk_fma_f32 v[10:11], v[50:51], v[8:9], v[12:13]
	v_and_b32_sdwa v9, v40, v198 dst_sel:DWORD dst_unused:UNUSED_PAD src0_sel:WORD_1 src1_sel:DWORD
	v_add3_u32 v12, v40, v9, s33
	v_and_b32_sdwa v9, v11, v198 dst_sel:DWORD dst_unused:UNUSED_PAD src0_sel:WORD_1 src1_sel:DWORD
	v_and_b32_sdwa v13, v10, v198 dst_sel:DWORD dst_unused:UNUSED_PAD src0_sel:WORD_1 src1_sel:DWORD
	v_and_b32_sdwa v8, v41, v198 dst_sel:DWORD dst_unused:UNUSED_PAD src0_sel:WORD_1 src1_sel:DWORD
	v_add3_u32 v9, v11, v9, s33
	v_add3_u32 v13, v10, v13, s33
	v_add3_u32 v8, v41, v8, s33
	v_and_b32_e32 v9, 0xffff0000, v9
	v_and_b32_e32 v13, 0xffff0000, v13
	v_or_b32_sdwa v9, v9, v8 dst_sel:DWORD dst_unused:UNUSED_PAD src0_sel:DWORD src1_sel:WORD_1
	v_or_b32_sdwa v8, v13, v12 dst_sel:DWORD dst_unused:UNUSED_PAD src0_sel:DWORD src1_sel:WORD_1
	global_store_dwordx2 v[26:27], v[8:9], off
	v_add_u32_e32 v12, v62, v63
	v_mov_b32_e32 v8, v40
	v_mov_b32_e32 v9, v10
	v_mov_b32_e32 v10, v41
	ds_write_b128 v12, v[8:11]
	v_pk_mul_f32 v[12:13], v[38:39], v[32:33] op_sel_hi:[1,0]
	v_mov_b32_e32 v38, v232
	v_mov_b32_e32 v39, v234
	v_pk_mul_f32 v[12:13], v[12:13], v[38:39]
	s_waitcnt lgkmcnt(0)
; __device__ __forceinline__ unsigned pack2(float a, float b) { return (unsigned)f2bf(a) | ((unsigned)f2bf(b) << 16); }
; __device__ __forceinline__ void router_rows(const Params& p, char* smem, int l, int nrows) {
;     ...
;       const int rl = wid * 2 + rr;
;       const int row = grp * 8 + rl;
;       const float* src = XR + (size_t)row * 1024;
;       int v = row < MLAT ? (row >> 13) : 2;
;       const float* mods = (const float*)(ws + OFF_MODS) + (l * 3 + v) * 6144;
;       float4 xv[4];
;       float ss = 0.f;
; #pragma unroll
;       for (int q = 0; q < 4; ++q) {
;         xv[q] = *(const float4*)&src[lane * 4 + 256 * q];
;         ss += xv[q].x * xv[q].x + xv[q].y * xv[q].y + xv[q].z * xv[q].z + xv[q].w * xv[q].w;
;       }
;     ...
; #pragma unroll
;       for (int q = 0; q < 4; ++q) {
;         int col = lane * 4 + 256 * q;
;         float4 w = *(const float4*)&nw[col];
;         float4 sh = *(const float4*)&mods[3072 + col];
;         float4 sc = *(const float4*)&mods[4096 + col];
;         float h0 = xv[q].x * rstd * w.x * (1.f + sc.x) + sh.x;
;         float h1 = xv[q].y * rstd * w.y * (1.f + sc.y) + sh.y;
;         float h2 = xv[q].z * rstd * w.z * (1.f + sc.z) + sh.z;
;         float h3 = xv[q].w * rstd * w.w * (1.f + sc.w) + sh.w;
;         uint2 o; o.x = pack2(h0, h1); o.y = pack2(h2, h3);
;         *(uint2*)&H2[(size_t)row * 1024 + col] = o;
;         *(float4*)&Hs[(col >> 2) * 36 + rl * 4] = make_float4(h0, h1, h2, h3);
;       }
	v_mov_b32_e32 v38, v244
	v_mov_b32_e32 v39, v246
	v_pk_add_f32 v[38:39], v[38:39], 1.0 op_sel_hi:[1,0]
	v_mov_b32_e32 v48, v240
	v_mov_b32_e32 v49, v242
	v_mov_b32_e32 v10, v233
	v_mov_b32_e32 v46, v245
	v_pk_fma_f32 v[12:13], v[12:13], v[38:39], v[48:49]
	v_mov_b32_e32 v11, v235
	v_pk_mul_f32 v[6:7], v[6:7], v[10:11]
	v_mov_b32_e32 v47, v247
	v_pk_add_f32 v[8:9], v[46:47], 1.0 op_sel_hi:[1,0]
	v_mov_b32_e32 v42, v241
	v_mov_b32_e32 v43, v243
	v_pk_fma_f32 v[8:9], v[6:7], v[8:9], v[42:43]
	v_and_b32_sdwa v7, v12, v198 dst_sel:DWORD dst_unused:UNUSED_PAD src0_sel:WORD_1 src1_sel:DWORD
	v_add3_u32 v10, v12, v7, s33
	v_and_b32_sdwa v7, v9, v198 dst_sel:DWORD dst_unused:UNUSED_PAD src0_sel:WORD_1 src1_sel:DWORD
	v_and_b32_sdwa v11, v8, v198 dst_sel:DWORD dst_unused:UNUSED_PAD src0_sel:WORD_1 src1_sel:DWORD
	v_and_b32_sdwa v6, v13, v198 dst_sel:DWORD dst_unused:UNUSED_PAD src0_sel:WORD_1 src1_sel:DWORD
	v_add3_u32 v7, v9, v7, s33
	v_add3_u32 v11, v8, v11, s33
	v_add3_u32 v6, v13, v6, s33
	v_and_b32_e32 v7, 0xffff0000, v7
	v_and_b32_e32 v11, 0xffff0000, v11
	v_or_b32_sdwa v7, v7, v6 dst_sel:DWORD dst_unused:UNUSED_PAD src0_sel:DWORD src1_sel:WORD_1
	v_or_b32_sdwa v6, v11, v10 dst_sel:DWORD dst_unused:UNUSED_PAD src0_sel:DWORD src1_sel:WORD_1
	global_store_dwordx2 v[26:27], v[6:7], off offset:512
	v_add_u32_e32 v10, v62, v64
	v_mov_b32_e32 v6, v12
	v_mov_b32_e32 v7, v8
	v_mov_b32_e32 v8, v13
	ds_write_b128 v10, v[6:9]
	global_load_dwordx4 v[186:189], v[28:29], off offset:2048
	global_load_dwordx4 v[190:193], v[18:19], off offset:3072
	global_load_dwordx4 v[212:215], v[30:31], off offset:3072
	global_load_dwordx4 v[216:219], v[28:29], off offset:3072
	s_waitcnt vmcnt(0)
	v_mov_b32_e32 v42, v248
	v_mov_b32_e32 v43, v250
	v_pk_mul_f32 v[36:37], v[36:37], v[42:43]
	s_waitcnt lgkmcnt(0)
	v_mov_b32_e32 v42, v186
	v_mov_b32_e32 v43, v188
	v_pk_add_f32 v[42:43], v[42:43], 1.0 op_sel_hi:[1,0]
	v_mov_b32_e32 v44, v252
	v_mov_b32_e32 v45, v254
	v_mov_b32_e32 v8, v249
	v_mov_b32_e32 v40, v187
	v_pk_fma_f32 v[36:37], v[36:37], v[42:43], v[44:45]
	v_mov_b32_e32 v9, v251
	v_pk_mul_f32 v[6:7], v[34:35], v[8:9]
	v_mov_b32_e32 v41, v189
	v_pk_add_f32 v[8:9], v[40:41], 1.0 op_sel_hi:[1,0]
	v_mov_b32_e32 v12, v253
	v_mov_b32_e32 v13, v255
	v_pk_fma_f32 v[8:9], v[6:7], v[8:9], v[12:13]
	v_and_b32_sdwa v7, v36, v198 dst_sel:DWORD dst_unused:UNUSED_PAD src0_sel:WORD_1 src1_sel:DWORD
	v_add3_u32 v10, v36, v7, s33
	v_and_b32_sdwa v7, v9, v198 dst_sel:DWORD dst_unused:UNUSED_PAD src0_sel:WORD_1 src1_sel:DWORD
	v_and_b32_sdwa v11, v8, v198 dst_sel:DWORD dst_unused:UNUSED_PAD src0_sel:WORD_1 src1_sel:DWORD
	v_and_b32_sdwa v6, v37, v198 dst_sel:DWORD dst_unused:UNUSED_PAD src0_sel:WORD_1 src1_sel:DWORD
	v_add3_u32 v7, v9, v7, s33
	v_add3_u32 v11, v8, v11, s33
	v_add3_u32 v6, v37, v6, s33
	v_and_b32_e32 v7, 0xffff0000, v7
	v_and_b32_e32 v11, 0xffff0000, v11
	v_or_b32_sdwa v7, v7, v6 dst_sel:DWORD dst_unused:UNUSED_PAD src0_sel:DWORD src1_sel:WORD_1
	v_or_b32_sdwa v6, v11, v10 dst_sel:DWORD dst_unused:UNUSED_PAD src0_sel:DWORD src1_sel:WORD_1
	global_store_dwordx2 v[26:27], v[6:7], off offset:1024
	v_add_u32_e32 v10, v62, v65
	v_mov_b32_e32 v6, v36
	v_mov_b32_e32 v7, v8
	v_mov_b32_e32 v8, v37
	ds_write_b128 v10, v[6:9]
	s_nop 0
	v_mov_b32_e32 v34, v228
	v_mov_b32_e32 v35, v230
	v_pk_mul_f32 v[34:35], v[34:35], v[32:33] op_sel_hi:[1,0]
	v_mov_b32_e32 v4, v229
	v_mov_b32_e32 v5, v231
	v_pk_mul_f32 v[2:3], v[4:5], v[32:33] op_sel_hi:[1,0]
	v_mov_b32_e32 v36, v190
	v_mov_b32_e32 v37, v192
	v_pk_mul_f32 v[34:35], v[34:35], v[36:37]
	s_waitcnt lgkmcnt(0)
	v_mov_b32_e32 v36, v216
	v_mov_b32_e32 v37, v218
	v_pk_add_f32 v[36:37], v[36:37], 1.0 op_sel_hi:[1,0]
	v_mov_b32_e32 v38, v212
	v_mov_b32_e32 v39, v214
	v_mov_b32_e32 v8, v191
	v_mov_b32_e32 v30, v217
	v_pk_fma_f32 v[34:35], v[34:35], v[36:37], v[38:39]
	v_mov_b32_e32 v9, v193
	v_pk_mul_f32 v[2:3], v[2:3], v[8:9]
	v_mov_b32_e32 v31, v219
	v_pk_add_f32 v[4:5], v[30:31], 1.0 op_sel_hi:[1,0]
	v_mov_b32_e32 v12, v213
	v_mov_b32_e32 v13, v215
	v_pk_fma_f32 v[4:5], v[2:3], v[4:5], v[12:13]
	v_and_b32_sdwa v3, v34, v198 dst_sel:DWORD dst_unused:UNUSED_PAD src0_sel:WORD_1 src1_sel:DWORD
	v_add3_u32 v6, v34, v3, s33
	v_and_b32_sdwa v3, v5, v198 dst_sel:DWORD dst_unused:UNUSED_PAD src0_sel:WORD_1 src1_sel:DWORD
	v_and_b32_sdwa v7, v4, v198 dst_sel:DWORD dst_unused:UNUSED_PAD src0_sel:WORD_1 src1_sel:DWORD
	v_and_b32_sdwa v2, v35, v198 dst_sel:DWORD dst_unused:UNUSED_PAD src0_sel:WORD_1 src1_sel:DWORD
	v_add3_u32 v3, v5, v3, s33
	v_add3_u32 v7, v4, v7, s33
	v_add3_u32 v2, v35, v2, s33
	v_and_b32_e32 v3, 0xffff0000, v3
	v_and_b32_e32 v7, 0xffff0000, v7
	v_or_b32_sdwa v3, v3, v2 dst_sel:DWORD dst_unused:UNUSED_PAD src0_sel:DWORD src1_sel:WORD_1
	v_or_b32_sdwa v2, v7, v6 dst_sel:DWORD dst_unused:UNUSED_PAD src0_sel:DWORD src1_sel:WORD_1
	global_store_dwordx2 v[26:27], v[2:3], off offset:1536
	v_add_u32_e32 v6, v62, v66
	v_mov_b32_e32 v2, v34
	v_mov_b32_e32 v3, v4
	v_mov_b32_e32 v4, v35
	ds_write_b128 v6, v[2:5]
	v_add_u32_e32 v4, s6, v67
	v_min_i32_e32 v2, 0x4000, v4
	v_ashrrev_i32_e32 v2, 13, v2
	v_add_u32_e32 v2, s8, v2
	v_mul_lo_u32 v6, v2, s7
	v_ashrrev_i32_e32 v7, 31, v6
	v_lshl_add_u64 v[28:29], v[6:7], 2, v[22:23]
	v_add_co_u32_e32 v30, vcc, s5, v28
	v_ashrrev_i32_e32 v5, 31, v4
	s_nop 0
	v_addc_co_u32_e32 v31, vcc, 0, v29, vcc
	v_lshlrev_b64 v[2:3], 12, v[4:5]
	v_add_co_u32_e32 v28, vcc, s91, v28
	v_lshl_add_u64 v[2:3], v[20:21], 0, v[2:3]
	s_nop 0
	v_addc_co_u32_e32 v29, vcc, 0, v29, vcc
	global_load_dwordx4 v[186:189], v[2:3], off
	global_load_dwordx4 v[190:193], v[18:19], off
	global_load_dwordx4 v[216:219], v[30:31], off
	global_load_dwordx4 v[220:223], v[28:29], off
	global_load_dwordx4 v[224:227], v[2:3], off offset:1024
	global_load_dwordx4 v[228:231], v[2:3], off offset:2048
	global_load_dwordx4 v[232:235], v[2:3], off offset:3072
	global_load_dwordx4 v[240:243], v[18:19], off offset:1024
	global_load_dwordx4 v[244:247], v[30:31], off offset:1024
	global_load_dwordx4 v[248:251], v[28:29], off offset:1024
	global_load_dwordx4 v[252:255], v[18:19], off offset:2048
	s_waitcnt vmcnt(0)
; __device__ __forceinline__ unsigned pack2(float a, float b) { return (unsigned)f2bf(a) | ((unsigned)f2bf(b) << 16); }
; __device__ __forceinline__ void router_rows(const Params& p, char* smem, int l, int nrows) {
;     ...
;       float4 xv[4];
;       float ss = 0.f;
; #pragma unroll
;       for (int q = 0; q < 4; ++q) {
;         xv[q] = *(const float4*)&src[lane * 4 + 256 * q];
;         ss += xv[q].x * xv[q].x + xv[q].y * xv[q].y + xv[q].z * xv[q].z + xv[q].w * xv[q].w;
;       }
;       ss = wave_sum(ss);
;       float rstd = rsqrtf(ss * (1.f / 1024.f) + EPSF);
; #pragma unroll
;       for (int q = 0; q < 4; ++q) {
;         int col = lane * 4 + 256 * q;
;         float4 w = *(const float4*)&nw[col];
;         float4 sh = *(const float4*)&mods[3072 + col];
;         float4 sc = *(const float4*)&mods[4096 + col];
;         float h0 = xv[q].x * rstd * w.x * (1.f + sc.x) + sh.x;
;         float h1 = xv[q].y * rstd * w.y * (1.f + sc.y) + sh.y;
;         float h2 = xv[q].z * rstd * w.z * (1.f + sc.z) + sh.z;
;         float h3 = xv[q].w * rstd * w.w * (1.f + sc.w) + sh.w;
;         uint2 o; o.x = pack2(h0, h1); o.y = pack2(h2, h3);
;         *(uint2*)&H2[(size_t)row * 1024 + col] = o;
;         *(float4*)&Hs[(col >> 2) * 36 + rl * 4] = make_float4(h0, h1, h2, h3);
	v_lshlrev_b64 v[4:5], 11, v[4:5]
	v_lshl_add_u64 v[26:27], v[24:25], 0, v[4:5]
	s_waitcnt lgkmcnt(0)
	v_mov_b32_e32 v40, v186
	v_mov_b32_e32 v42, v190
	v_mov_b32_e32 v43, v192
	v_mov_b32_e32 v4, v220
	v_mov_b32_e32 v5, v222
	v_pk_add_f32 v[44:45], v[4:5], 1.0 op_sel_hi:[1,0]
	v_mov_b32_e32 v8, v191
	v_mov_b32_e32 v72, v221
	v_mov_b32_e32 v46, v216
	v_mov_b32_e32 v48, v187
	v_mov_b32_e32 v73, v223
	v_pk_add_f32 v[50:51], v[72:73], 1.0 op_sel_hi:[1,0]
	v_mov_b32_e32 v10, v186
	v_mov_b32_e32 v34, v187
	v_mov_b32_e32 v47, v218
	v_mov_b32_e32 v12, v217
	v_mov_b32_e32 v41, v188
	v_mov_b32_e32 v49, v189
	s_waitcnt lgkmcnt(0)
	v_mov_b32_e32 v35, v225
	v_mov_b32_e32 v11, v224
	v_pk_mul_f32 v[34:35], v[34:35], v[34:35]
	v_mov_b32_e32 v38, v224
	v_pk_fma_f32 v[10:11], v[10:11], v[10:11], v[34:35]
	v_mov_b32_e32 v35, v226
	v_mov_b32_e32 v39, v226
	v_mov_b32_e32 v6, v225
	v_mov_b32_e32 v34, v188
	v_pk_fma_f32 v[10:11], v[34:35], v[34:35], v[10:11]
	v_mov_b32_e32 v34, v189
	v_mov_b32_e32 v35, v227
	v_pk_fma_f32 v[10:11], v[34:35], v[34:35], v[10:11]
	v_mov_b32_e32 v36, v228
	v_mov_b32_e32 v34, v229
	v_mov_b32_e32 v74, v228
	v_mov_b32_e32 v70, v229
	v_mov_b32_e32 v37, v230
	v_mov_b32_e32 v35, v231
	v_add_f32_e32 v10, v10, v11
	s_waitcnt lgkmcnt(0)
	v_mov_b32_e32 v71, v233
	v_mov_b32_e32 v75, v232
	v_pk_mul_f32 v[70:71], v[70:71], v[70:71]
	s_nop 0
	v_pk_fma_f32 v[70:71], v[74:75], v[74:75], v[70:71]
	v_mov_b32_e32 v74, v230
	v_mov_b32_e32 v75, v234
	v_pk_fma_f32 v[70:71], v[74:75], v[74:75], v[70:71]
	v_mov_b32_e32 v72, v231
	v_mov_b32_e32 v73, v235
	v_pk_fma_f32 v[70:71], v[72:73], v[72:73], v[70:71]
	s_nop 0
	v_add_f32_e32 v10, v10, v70
	v_add_f32_e32 v10, v10, v71
	ds_bpermute_b32 v11, v52, v10
	s_waitcnt lgkmcnt(0)
	v_add_f32_e32 v10, v10, v11
	ds_bpermute_b32 v11, v53, v10
	s_waitcnt lgkmcnt(0)
	v_add_f32_e32 v10, v10, v11
	ds_bpermute_b32 v11, v54, v10
	s_waitcnt lgkmcnt(0)
	v_add_f32_e32 v10, v10, v11
	ds_bpermute_b32 v11, v55, v10
	s_waitcnt lgkmcnt(0)
	v_add_f32_e32 v10, v10, v11
	ds_bpermute_b32 v11, v56, v10
	s_waitcnt lgkmcnt(0)
	v_add_f32_e32 v10, v10, v11
	ds_bpermute_b32 v11, v57, v10
	s_waitcnt lgkmcnt(0)
	v_add_f32_e32 v10, v10, v11
	v_fmamk_f32 v10, v10, 0x3a800000, v197
	v_cmp_gt_f32_e32 vcc, s4, v10
	v_mul_f32_e32 v11, 0x4b800000, v10
	s_mov_b64 s[4:5], 0
	v_cndmask_b32_e32 v10, v10, v11, vcc
	v_rsq_f32_e32 v10, v10
	s_nop 0
	v_mul_f32_e32 v11, 0x45800000, v10
	v_cndmask_b32_e32 v32, v10, v11, vcc
	v_pk_mul_f32 v[10:11], v[40:41], v[32:33] op_sel_hi:[1,0]
	v_mov_b32_e32 v7, v227
	v_pk_mul_f32 v[6:7], v[6:7], v[32:33] op_sel_hi:[1,0]
	v_pk_mul_f32 v[10:11], v[42:43], v[10:11]
	v_pk_mul_f32 v[36:37], v[36:37], v[32:33] op_sel_hi:[1,0]
	v_pk_fma_f32 v[40:41], v[44:45], v[10:11], v[46:47]
	v_pk_mul_f32 v[10:11], v[48:49], v[32:33] op_sel_hi:[1,0]
	v_pk_mul_f32 v[34:35], v[34:35], v[32:33] op_sel_hi:[1,0]
	v_mov_b32_e32 v9, v193
	v_pk_mul_f32 v[8:9], v[8:9], v[10:11]
	s_nop 0
	v_mov_b32_e32 v13, v219
	v_pk_fma_f32 v[10:11], v[50:51], v[8:9], v[12:13]
	v_and_b32_sdwa v9, v40, v198 dst_sel:DWORD dst_unused:UNUSED_PAD src0_sel:WORD_1 src1_sel:DWORD
	v_add3_u32 v12, v40, v9, s33
	v_and_b32_sdwa v9, v11, v198 dst_sel:DWORD dst_unused:UNUSED_PAD src0_sel:WORD_1 src1_sel:DWORD
	v_and_b32_sdwa v13, v10, v198 dst_sel:DWORD dst_unused:UNUSED_PAD src0_sel:WORD_1 src1_sel:DWORD
	v_and_b32_sdwa v8, v41, v198 dst_sel:DWORD dst_unused:UNUSED_PAD src0_sel:WORD_1 src1_sel:DWORD
	v_add3_u32 v9, v11, v9, s33
	v_add3_u32 v13, v10, v13, s33
	v_add3_u32 v8, v41, v8, s33
	v_and_b32_e32 v9, 0xffff0000, v9
	v_and_b32_e32 v13, 0xffff0000, v13
	v_or_b32_sdwa v9, v9, v8 dst_sel:DWORD dst_unused:UNUSED_PAD src0_sel:DWORD src1_sel:WORD_1
	v_or_b32_sdwa v8, v13, v12 dst_sel:DWORD dst_unused:UNUSED_PAD src0_sel:DWORD src1_sel:WORD_1
	global_store_dwordx2 v[26:27], v[8:9], off
	v_add_u32_e32 v12, v68, v63
	v_mov_b32_e32 v8, v40
	v_mov_b32_e32 v9, v10
	v_mov_b32_e32 v10, v41
	ds_write_b128 v12, v[8:11]
	v_pk_mul_f32 v[12:13], v[38:39], v[32:33] op_sel_hi:[1,0]
	v_mov_b32_e32 v38, v240
	v_mov_b32_e32 v39, v242
	v_pk_mul_f32 v[12:13], v[12:13], v[38:39]
	s_waitcnt lgkmcnt(0)
; __device__ __forceinline__ unsigned pack2(float a, float b) { return (unsigned)f2bf(a) | ((unsigned)f2bf(b) << 16); }
; __device__ __forceinline__ void router_rows(const Params& p, char* smem, int l, int nrows) {
;     ...
; #pragma unroll
;       for (int q = 0; q < 4; ++q) {
;         int col = lane * 4 + 256 * q;
;         float4 w = *(const float4*)&nw[col];
;         float4 sh = *(const float4*)&mods[3072 + col];
;         float4 sc = *(const float4*)&mods[4096 + col];
;         float h0 = xv[q].x * rstd * w.x * (1.f + sc.x) + sh.x;
;         float h1 = xv[q].y * rstd * w.y * (1.f + sc.y) + sh.y;
;         float h2 = xv[q].z * rstd * w.z * (1.f + sc.z) + sh.z;
;         float h3 = xv[q].w * rstd * w.w * (1.f + sc.w) + sh.w;
;         uint2 o; o.x = pack2(h0, h1); o.y = pack2(h2, h3);
;         *(uint2*)&H2[(size_t)row * 1024 + col] = o;
;         *(float4*)&Hs[(col >> 2) * 36 + rl * 4] = make_float4(h0, h1, h2, h3);
;       }
;     }
;     __syncthreads();
;     {
;       const int e = tid & 15, ks = tid >> 4;
	v_mov_b32_e32 v38, v248
	v_mov_b32_e32 v39, v250
	v_pk_add_f32 v[38:39], v[38:39], 1.0 op_sel_hi:[1,0]
	v_mov_b32_e32 v48, v244
	v_mov_b32_e32 v49, v246
	v_mov_b32_e32 v10, v241
	v_mov_b32_e32 v46, v249
	v_pk_fma_f32 v[12:13], v[12:13], v[38:39], v[48:49]
	v_mov_b32_e32 v11, v243
	v_pk_mul_f32 v[6:7], v[6:7], v[10:11]
	v_mov_b32_e32 v47, v251
	v_pk_add_f32 v[8:9], v[46:47], 1.0 op_sel_hi:[1,0]
	v_mov_b32_e32 v42, v245
	v_mov_b32_e32 v43, v247
	v_pk_fma_f32 v[8:9], v[6:7], v[8:9], v[42:43]
	v_and_b32_sdwa v7, v12, v198 dst_sel:DWORD dst_unused:UNUSED_PAD src0_sel:WORD_1 src1_sel:DWORD
	v_add3_u32 v10, v12, v7, s33
	v_and_b32_sdwa v7, v9, v198 dst_sel:DWORD dst_unused:UNUSED_PAD src0_sel:WORD_1 src1_sel:DWORD
	v_and_b32_sdwa v11, v8, v198 dst_sel:DWORD dst_unused:UNUSED_PAD src0_sel:WORD_1 src1_sel:DWORD
	v_and_b32_sdwa v6, v13, v198 dst_sel:DWORD dst_unused:UNUSED_PAD src0_sel:WORD_1 src1_sel:DWORD
	v_add3_u32 v7, v9, v7, s33
	v_add3_u32 v11, v8, v11, s33
	v_add3_u32 v6, v13, v6, s33
	v_and_b32_e32 v7, 0xffff0000, v7
	v_and_b32_e32 v11, 0xffff0000, v11
	v_or_b32_sdwa v7, v7, v6 dst_sel:DWORD dst_unused:UNUSED_PAD src0_sel:DWORD src1_sel:WORD_1
	v_or_b32_sdwa v6, v11, v10 dst_sel:DWORD dst_unused:UNUSED_PAD src0_sel:DWORD src1_sel:WORD_1
	global_store_dwordx2 v[26:27], v[6:7], off offset:512
	v_add_u32_e32 v10, v68, v64
	v_mov_b32_e32 v6, v12
	v_mov_b32_e32 v7, v8
	v_mov_b32_e32 v8, v13
	ds_write_b128 v10, v[6:9]
	global_load_dwordx4 v[186:189], v[30:31], off offset:2048
	global_load_dwordx4 v[190:193], v[28:29], off offset:2048
	global_load_dwordx4 v[212:215], v[18:19], off offset:3072
	global_load_dwordx4 v[216:219], v[30:31], off offset:3072
	global_load_dwordx4 v[220:223], v[28:29], off offset:3072
	s_waitcnt vmcnt(0)
	v_mov_b32_e32 v42, v252
	v_mov_b32_e32 v43, v254
	v_pk_mul_f32 v[36:37], v[36:37], v[42:43]
	s_waitcnt lgkmcnt(0)
	v_mov_b32_e32 v42, v190
	v_mov_b32_e32 v43, v192
	v_pk_add_f32 v[42:43], v[42:43], 1.0 op_sel_hi:[1,0]
	v_mov_b32_e32 v44, v186
	v_mov_b32_e32 v45, v188
	v_mov_b32_e32 v8, v253
	v_mov_b32_e32 v40, v191
	v_pk_fma_f32 v[36:37], v[36:37], v[42:43], v[44:45]
	v_mov_b32_e32 v9, v255
	v_pk_mul_f32 v[6:7], v[34:35], v[8:9]
	v_mov_b32_e32 v41, v193
	v_pk_add_f32 v[8:9], v[40:41], 1.0 op_sel_hi:[1,0]
	v_mov_b32_e32 v12, v187
	v_mov_b32_e32 v13, v189
	v_pk_fma_f32 v[8:9], v[6:7], v[8:9], v[12:13]
	v_and_b32_sdwa v7, v36, v198 dst_sel:DWORD dst_unused:UNUSED_PAD src0_sel:WORD_1 src1_sel:DWORD
	v_add3_u32 v10, v36, v7, s33
	v_and_b32_sdwa v7, v9, v198 dst_sel:DWORD dst_unused:UNUSED_PAD src0_sel:WORD_1 src1_sel:DWORD
	v_and_b32_sdwa v11, v8, v198 dst_sel:DWORD dst_unused:UNUSED_PAD src0_sel:WORD_1 src1_sel:DWORD
	v_and_b32_sdwa v6, v37, v198 dst_sel:DWORD dst_unused:UNUSED_PAD src0_sel:WORD_1 src1_sel:DWORD
	v_add3_u32 v7, v9, v7, s33
	v_add3_u32 v11, v8, v11, s33
	v_add3_u32 v6, v37, v6, s33
	v_and_b32_e32 v7, 0xffff0000, v7
	v_and_b32_e32 v11, 0xffff0000, v11
	v_or_b32_sdwa v7, v7, v6 dst_sel:DWORD dst_unused:UNUSED_PAD src0_sel:DWORD src1_sel:WORD_1
	v_or_b32_sdwa v6, v11, v10 dst_sel:DWORD dst_unused:UNUSED_PAD src0_sel:DWORD src1_sel:WORD_1
	global_store_dwordx2 v[26:27], v[6:7], off offset:1024
	v_add_u32_e32 v10, v68, v65
	v_mov_b32_e32 v6, v36
	v_mov_b32_e32 v7, v8
	v_mov_b32_e32 v8, v37
	ds_write_b128 v10, v[6:9]
	s_nop 0
	v_mov_b32_e32 v34, v232
	v_mov_b32_e32 v35, v234
	v_pk_mul_f32 v[34:35], v[34:35], v[32:33] op_sel_hi:[1,0]
	v_mov_b32_e32 v4, v233
	v_mov_b32_e32 v5, v235
	v_pk_mul_f32 v[2:3], v[4:5], v[32:33] op_sel_hi:[1,0]
	v_mov_b32_e32 v36, v212
	v_mov_b32_e32 v37, v214
	v_pk_mul_f32 v[34:35], v[34:35], v[36:37]
	s_waitcnt lgkmcnt(0)
	v_mov_b32_e32 v36, v220
	v_mov_b32_e32 v37, v222
	v_pk_add_f32 v[36:37], v[36:37], 1.0 op_sel_hi:[1,0]
	v_mov_b32_e32 v38, v216
	v_mov_b32_e32 v39, v218
	v_mov_b32_e32 v8, v213
	v_mov_b32_e32 v30, v221
	v_pk_fma_f32 v[34:35], v[34:35], v[36:37], v[38:39]
	v_mov_b32_e32 v9, v215
	v_pk_mul_f32 v[2:3], v[2:3], v[8:9]
	v_mov_b32_e32 v31, v223
	v_pk_add_f32 v[4:5], v[30:31], 1.0 op_sel_hi:[1,0]
	v_mov_b32_e32 v12, v217
	v_mov_b32_e32 v13, v219
	v_pk_fma_f32 v[4:5], v[2:3], v[4:5], v[12:13]
	v_and_b32_sdwa v3, v34, v198 dst_sel:DWORD dst_unused:UNUSED_PAD src0_sel:WORD_1 src1_sel:DWORD
	v_add3_u32 v6, v34, v3, s33
	v_and_b32_sdwa v3, v5, v198 dst_sel:DWORD dst_unused:UNUSED_PAD src0_sel:WORD_1 src1_sel:DWORD
	v_and_b32_sdwa v7, v4, v198 dst_sel:DWORD dst_unused:UNUSED_PAD src0_sel:WORD_1 src1_sel:DWORD
	v_and_b32_sdwa v2, v35, v198 dst_sel:DWORD dst_unused:UNUSED_PAD src0_sel:WORD_1 src1_sel:DWORD
	v_add3_u32 v3, v5, v3, s33
	v_add3_u32 v7, v4, v7, s33
	v_add3_u32 v2, v35, v2, s33
	v_and_b32_e32 v3, 0xffff0000, v3
	v_and_b32_e32 v7, 0xffff0000, v7
	v_or_b32_sdwa v3, v3, v2 dst_sel:DWORD dst_unused:UNUSED_PAD src0_sel:DWORD src1_sel:WORD_1
	v_or_b32_sdwa v2, v7, v6 dst_sel:DWORD dst_unused:UNUSED_PAD src0_sel:DWORD src1_sel:WORD_1
	global_store_dwordx2 v[26:27], v[2:3], off offset:1536
	v_add_u32_e32 v6, v68, v66
	v_mov_b32_e32 v2, v34
	v_mov_b32_e32 v3, v4
	v_mov_b32_e32 v4, v35
	ds_write_b128 v6, v[2:5]
	v_mov_b32_e32 v6, 0
	v_mov_b32_e32 v10, v0
	v_mov_b32_e32 v7, v6
	v_mov_b32_e32 v8, v6
	v_mov_b32_e32 v9, v6
	v_mov_b32_e32 v4, v6
	v_mov_b32_e32 v5, v6
	v_mov_b32_e32 v2, v6
	v_mov_b32_e32 v3, v6
	s_waitcnt lgkmcnt(0)
	v_mov_b32_e32 v11, v217
	v_mov_b32_e32 v28, v220
	v_mov_b32_e32 v29, v221
	s_barrier

; template <int NV>
; __device__ __forceinline__ void topk_body(char* smem, const unsigned* A, int* oi, float* og, int cap) {
;     ...
;     const unsigned cand = T | (1u << bit);
;     int c = 0;
; #pragma unroll
;     for (int q = 0; q < NV; ++q) c += (v[q] >= cand) ? 1 : 0;
; #pragma unroll
;     for (int o = 32; o > 0; o >>= 1) c += __shfl_xor(c, o);
;     int* rb = red + (bit & 1) * 4;
;     if (lane == 0) rb[wid] = c;
;     __syncthreads();
;     int tot = rb[0] + rb[1] + rb[2] + rb[3];
;     if (tot >= cap) T = cand;
;   }
.LBB0_1332:
	s_lshl_b32 s0, 1, s4
	v_or_b32_e32 v22, s0, v3
	s_waitcnt vmcnt(0)
	s_and_b32 s0, s5, 4
	s_lshl_b32 s8, s0, 2
	s_mov_b32 s100, 0
	v_cmp_ge_u32_e32 vcc, v53, v22
	s_bcnt1_i32_b64 s101, vcc
	s_add_u32 s100, s100, s101
	v_cmp_ge_u32_e32 vcc, v54, v22
	s_bcnt1_i32_b64 s101, vcc
	s_add_u32 s100, s100, s101
	v_cmp_ge_u32_e32 vcc, v51, v22
	s_bcnt1_i32_b64 s101, vcc
	s_add_u32 s100, s100, s101
	v_cmp_ge_u32_e32 vcc, v50, v22
	s_bcnt1_i32_b64 s101, vcc
	s_add_u32 s100, s100, s101
	v_cmp_ge_u32_e32 vcc, v48, v22
	s_bcnt1_i32_b64 s101, vcc
	s_add_u32 s100, s100, s101
	v_cmp_ge_u32_e32 vcc, v47, v22
	s_bcnt1_i32_b64 s101, vcc
	s_add_u32 s100, s100, s101
	v_cmp_ge_u32_e32 vcc, v45, v22
	s_bcnt1_i32_b64 s101, vcc
	s_add_u32 s100, s100, s101
	v_cmp_ge_u32_e32 vcc, v44, v22
	s_bcnt1_i32_b64 s101, vcc
	s_add_u32 s100, s100, s101
	v_cmp_ge_u32_e32 vcc, v42, v22
	s_bcnt1_i32_b64 s101, vcc
	s_add_u32 s100, s100, s101
	v_cmp_ge_u32_e32 vcc, v41, v22
	s_bcnt1_i32_b64 s101, vcc
	s_add_u32 s100, s100, s101
	v_cmp_ge_u32_e32 vcc, v39, v22
	s_bcnt1_i32_b64 s101, vcc
	s_add_u32 s100, s100, s101
	v_cmp_ge_u32_e32 vcc, v38, v22
	s_bcnt1_i32_b64 s101, vcc
	s_add_u32 s100, s100, s101
	v_cmp_ge_u32_e32 vcc, v36, v22
	s_bcnt1_i32_b64 s101, vcc
	s_add_u32 s100, s100, s101
	v_cmp_ge_u32_e32 vcc, v35, v22
	s_bcnt1_i32_b64 s101, vcc
	s_add_u32 s100, s100, s101
	v_cmp_ge_u32_e32 vcc, v33, v22
	s_bcnt1_i32_b64 s101, vcc
	s_add_u32 s100, s100, s101
	v_cmp_ge_u32_e32 vcc, v32, v22
	s_bcnt1_i32_b64 s101, vcc
	s_add_u32 s100, s100, s101
	v_cmp_ge_u32_e32 vcc, v30, v22
	s_bcnt1_i32_b64 s101, vcc
	s_add_u32 s100, s100, s101
	v_cmp_ge_u32_e32 vcc, v29, v22
	s_bcnt1_i32_b64 s101, vcc
	s_add_u32 s100, s100, s101
	v_cmp_ge_u32_e32 vcc, v27, v22
	s_bcnt1_i32_b64 s101, vcc
	s_add_u32 s100, s100, s101
	v_cmp_ge_u32_e32 vcc, v26, v22
	s_bcnt1_i32_b64 s101, vcc
	s_add_u32 s100, s100, s101
	v_cmp_ge_u32_e32 vcc, v24, v22
	s_bcnt1_i32_b64 s101, vcc
	s_add_u32 s100, s100, s101
	v_cmp_ge_u32_e32 vcc, v23, v22
	s_bcnt1_i32_b64 s101, vcc
	s_add_u32 s100, s100, s101
	v_cmp_ge_u32_e32 vcc, v18, v22
	s_bcnt1_i32_b64 s101, vcc
	s_add_u32 s100, s100, s101
	v_cmp_ge_u32_e32 vcc, v17, v22
	s_bcnt1_i32_b64 s101, vcc
	s_add_u32 s100, s100, s101
	v_cmp_ge_u32_e32 vcc, v15, v22
	s_bcnt1_i32_b64 s101, vcc
	s_add_u32 s100, s100, s101
	v_cmp_ge_u32_e32 vcc, v14, v22
	s_bcnt1_i32_b64 s101, vcc
	s_add_u32 s100, s100, s101
	v_cmp_ge_u32_e32 vcc, v13, v22
	s_bcnt1_i32_b64 s101, vcc
	s_add_u32 s100, s100, s101
	v_cmp_ge_u32_e32 vcc, v12, v22
	s_bcnt1_i32_b64 s101, vcc
	s_add_u32 s100, s100, s101
	v_cmp_ge_u32_e32 vcc, v11, v22
	s_bcnt1_i32_b64 s101, vcc
	s_add_u32 s100, s100, s101
	v_cmp_ge_u32_e32 vcc, v10, v22
	s_bcnt1_i32_b64 s101, vcc
	s_add_u32 s100, s100, s101
	v_cmp_ge_u32_e32 vcc, v7, v22
	s_bcnt1_i32_b64 s101, vcc
	s_add_u32 s100, s100, s101
	v_cmp_ge_u32_e32 vcc, v0, v22
	s_bcnt1_i32_b64 s101, vcc
	s_add_u32 s100, s100, s101
	v_mov_b32_e32 v25, s100
	s_and_saveexec_b64 s[0:1], s[6:7]
	s_cbranch_execz .LBB0_1331
	v_lshl_add_u32 v28, v8, 2, s8
	ds_write_b32 v28, v25
	s_branch .LBB0_1331

; __global__ void __launch_bounds__(256, 2) fwd_megakernel(Params p) {
	.amdhsa_kernel _Z14fwd_megakernel6Params
		.amdhsa_group_segment_fixed_size 65492
		.amdhsa_private_segment_fixed_size 0
		.amdhsa_kernarg_size 496
		.amdhsa_user_sgpr_count 2
		.amdhsa_user_sgpr_dispatch_ptr 0
		.amdhsa_user_sgpr_queue_ptr 0
		.amdhsa_user_sgpr_kernarg_segment_ptr 1
		.amdhsa_user_sgpr_dispatch_id 0
		.amdhsa_user_sgpr_kernarg_preload_length 0
		.amdhsa_user_sgpr_kernarg_preload_offset 0
		.amdhsa_user_sgpr_private_segment_size 0
		.amdhsa_uses_dynamic_stack 0
		.amdhsa_enable_private_segment 0
		.amdhsa_system_sgpr_workgroup_id_x 1
		.amdhsa_system_sgpr_workgroup_id_y 0
		.amdhsa_system_sgpr_workgroup_id_z 0
		.amdhsa_system_sgpr_workgroup_info 0
		.amdhsa_system_vgpr_workitem_id 2
		.amdhsa_next_free_vgpr 256
		.amdhsa_next_free_sgpr 102
		.amdhsa_accum_offset 256
		.amdhsa_reserve_vcc 1
		.amdhsa_float_round_mode_32 0
		.amdhsa_float_round_mode_16_64 0
		.amdhsa_float_denorm_mode_32 3
		.amdhsa_float_denorm_mode_16_64 3
		.amdhsa_dx10_clamp 1
		.amdhsa_ieee_mode 1
		.amdhsa_fp16_overflow 0
		.amdhsa_tg_split 0
		.amdhsa_exception_fp_ieee_invalid_op 0
		.amdhsa_exception_fp_denorm_src 0
		.amdhsa_exception_fp_ieee_div_zero 0
		.amdhsa_exception_fp_ieee_overflow 0
		.amdhsa_exception_fp_ieee_underflow 0
		.amdhsa_exception_fp_ieee_inexact 0
		.amdhsa_exception_int_div_zero 0
	.end_amdhsa_kernel

; __global__ void __launch_bounds__(256, 2) fwd_megakernel(Params p) {
amdhsa.kernels:
  - .agpr_count:     0
    .args:
      - .offset:         0
        .size:           240
        .value_kind:     by_value
      - .offset:         240
        .size:           4
        .value_kind:     hidden_block_count_x
      - .offset:         244
        .size:           4
        .value_kind:     hidden_block_count_y
      - .offset:         248
        .size:           4
        .value_kind:     hidden_block_count_z
      - .offset:         252
        .size:           2
        .value_kind:     hidden_group_size_x
      - .offset:         254
        .size:           2
        .value_kind:     hidden_group_size_y
      - .offset:         256
        .size:           2
        .value_kind:     hidden_group_size_z
      - .offset:         258
        .size:           2
        .value_kind:     hidden_remainder_x
      - .offset:         260
        .size:           2
        .value_kind:     hidden_remainder_y
      - .offset:         262
        .size:           2
        .value_kind:     hidden_remainder_z
      - .offset:         280
        .size:           8
        .value_kind:     hidden_global_offset_x
      - .offset:         288
        .size:           8
        .value_kind:     hidden_global_offset_y
      - .offset:         296
        .size:           8
        .value_kind:     hidden_global_offset_z
      - .offset:         304
        .size:           2
        .value_kind:     hidden_grid_dims
      - .offset:         328
        .size:           8
        .value_kind:     hidden_multigrid_sync_arg
    .group_segment_fixed_size: 65492
    .kernarg_segment_align: 8
    .kernarg_segment_size: 496
    .language:       OpenCL C
    .language_version:
      - 2
      - 0
    .max_flat_workgroup_size: 256
    .name:           _Z14fwd_megakernel6Params
    .private_segment_fixed_size: 0
    .sgpr_count:     108
    .sgpr_spill_count: 238
    .symbol:         _Z14fwd_megakernel6Params.kd
    .uniform_work_group_size: 1
    .uses_dynamic_stack: false
    .vgpr_count:     256
    .vgpr_spill_count: 0
    .wavefront_size: 64
